# counted lgkmcnt: SEL QK^T K-fragment LDS reads pipelined 3 deep (8 reads up front, lgkmcnt(4) steady state) instead of just-in-time
# speedup vs baseline: 1.0066x; 1.0066x over previous
; #define LAS __attribute__((address_space(3)))
; #define MFMA32(a, b, c) __builtin_amdgcn_mfma_f32_32x32x16_bf16((a), (b), (c), 0, 0, 0)
; template <int MODE> DI void attn_h1(AttnCtx& c, const bf16x8 (&q)[8], f32x16 (&o)[4], f32x16& s0, f32x16& s1, ldsp lds, int kbuf, int bbuf, int tj, int lane) {
;     ...
;             ldsp kl = lds + kbuf + r32 * KPITCH + h * 16;
; #pragma unroll
;             for (int e = 0; e < 16; ++e) { s0[e] = 0.f; s1[e] = 0.f; }
; #pragma unroll
;             for (int s = 0; s < 8; ++s) {
;                 const bf16x8 ka = *(const LAS bf16x8*)(kl + s * 32), kb = *(const LAS bf16x8*)(kl + 32 * KPITCH + s * 32);
;                 s0 = MFMA32(ka, q[s], s0); s1 = MFMA32(kb, q[s], s1);
;                 if (s == 3) asm volatile("" ::: "memory");
;             }
;     ...
;                 const int P0 = CMP ? tj * 1024 + 31 : tj * 64;
;                 const float dbase = (float)(c.t - P0 - PS * 4 * h);
;                 bool selbit = true;
;                 if (MODE == MD_SEL) selbit = ((*(const LAS unsigned*)(lds + A_SEL + c.qi * 16 + (tj >> 5) * 4) >> (tj & 31)) & 1u) != 0u;
;                 bool needmask = true;
;                 if (MODE == MD_WIN) needmask = (tj == c.mtile) || (tj + 8 == c.mtile);
;                 if (MODE == MD_SEL) needmask = (tj >= c.mtile);
.LBB0_909:
	s_add_i32 s2, s21, -1
	s_andn2_b64 vcc, exec, s[6:7]
	s_and_b32 s38, s2, 1
	s_cbranch_vccnz .LBB0_918
	s_sub_i32 s2, s22, 64
	s_cmp_lt_i32 s22, 64
	s_cselect_b32 s4, s22, s2
	s_cselect_b32 s3, s9, s11
	s_cselect_b32 s2, s8, s10
	s_lshr_b64 s[2:3], s[2:3], s4
	s_and_b32 s16, s2, 1
	s_cmp_eq_u64 s[16:17], 0
	s_cbranch_scc1 .LBB0_918
	s_mul_i32 s2, s38, 0x4400
	v_add_u32_e32 v0, s2, v205
	ds_read_b128 v[2:5], v0 offset:8704
	ds_read_b128 v[6:9], v0
	ds_read_b128 v[160:163], v0 offset:32
	ds_read_b128 v[164:167], v0 offset:8736
	ds_read_b128 v[168:171], v0 offset:64
	ds_read_b128 v[172:175], v0 offset:8768
	ds_read_b128 v[176:179], v0 offset:96
	ds_read_b128 v[180:183], v0 offset:8800
	s_ashr_i32 s2, s22, 3
	s_and_b32 s2, s2, -4
	s_waitcnt lgkmcnt(6)
	v_mfma_f32_32x32x16_bf16 v[82:97], v[6:9], v[98:101], 0
	s_mov_b64 s[4:5], -1
	s_cmp_lt_i32 s22, s0
	v_mfma_f32_32x32x16_bf16 v[2:17], v[2:5], v[98:101], 0
	s_waitcnt lgkmcnt(4)
	v_mfma_f32_32x32x16_bf16 v[82:97], v[160:163], v[102:105], v[82:97]
	v_mfma_f32_32x32x16_bf16 v[2:17], v[164:167], v[102:105], v[2:17]
	ds_read_b128 v[160:163], v0 offset:128
	ds_read_b128 v[164:167], v0 offset:8832
	s_waitcnt lgkmcnt(4)
	v_mfma_f32_32x32x16_bf16 v[82:97], v[168:171], v[106:109], v[82:97]
	v_mfma_f32_32x32x16_bf16 v[2:17], v[172:175], v[106:109], v[2:17]
	ds_read_b128 v[168:171], v0 offset:160
	ds_read_b128 v[172:175], v0 offset:8864
	s_waitcnt lgkmcnt(4)
	v_mfma_f32_32x32x16_bf16 v[82:97], v[176:179], v[110:113], v[82:97]
	v_mfma_f32_32x32x16_bf16 v[2:17], v[180:183], v[110:113], v[2:17]
	ds_read_b128 v[176:179], v0 offset:192
	ds_read_b128 v[180:183], v0 offset:8896
	s_waitcnt lgkmcnt(4)
	v_mfma_f32_32x32x16_bf16 v[82:97], v[160:163], v[114:117], v[82:97]
	v_mfma_f32_32x32x16_bf16 v[2:17], v[164:167], v[114:117], v[2:17]
	ds_read_b128 v[160:163], v0 offset:224
	ds_read_b128 v[164:167], v0 offset:8928
	s_waitcnt lgkmcnt(4)
	v_mfma_f32_32x32x16_bf16 v[82:97], v[168:171], v[118:121], v[82:97]
	v_mfma_f32_32x32x16_bf16 v[2:17], v[172:175], v[118:121], v[2:17]
	v_lshl_or_b32 v184, s22, 6, v204
	v_add_u32_e32 v185, s2, v212
	ds_read_b32 v185, v185
	s_waitcnt lgkmcnt(3)
	v_mfma_f32_32x32x16_bf16 v[82:97], v[176:179], v[122:125], v[82:97]
	v_mfma_f32_32x32x16_bf16 v[2:17], v[180:183], v[122:125], v[2:17]
	s_waitcnt lgkmcnt(1)
	v_mfma_f32_32x32x16_bf16 v[2:17], v[164:167], v[126:129], v[2:17]
	v_mfma_f32_32x32x16_bf16 v[82:97], v[160:163], v[126:129], v[82:97]
	v_sub_u32_e32 v160, v148, v184
	v_cvt_f32_i32_e32 v217, v160
	s_waitcnt lgkmcnt(0)
	v_lshrrev_b32_e32 v0, s22, v185
	v_and_b32_e32 v0, 1, v0
	v_cmp_eq_u32_e64 s[2:3], 1, v0
	s_nop 1
	s_cbranch_scc1 .LBB0_913
; template <int MODE> DI void attn_h1(AttnCtx& c, const bf16x8 (&q)[8], f32x16 (&o)[4], f32x16& s0, f32x16& s1, ldsp lds, int kbuf, int bbuf, int tj, int lane) {
;     ...
;                 if (needmask) {
; #pragma unroll
;                     for (int e = 0; e < 16; ++e) {
;                         const float d0 = dbase - (float)(PS * (8 * (e >> 2) + (e & 3))), d1 = d0 - (float)(PS * 32);
;                         bool v0 = d0 >= 0.f, v1 = d1 >= 0.f;
;                         if (MODE == MD_WIN) { v0 = v0 && d0 < 512.f; v1 = v1 && d1 < 512.f; }
;                         if (MODE == MD_SEL) { v0 = v0 && selbit; v1 = v1 && selbit; }
;                         s0[e] = v0 ? s0[e] - c.slope2 * d0 : NINF;
;                         s1[e] = v1 ? s1[e] - c.slope2 * d1 : NINF;
;                     }
	v_add_f32_e32 v161, 0xc2000000, v217
	v_cmp_lt_i32_e32 vcc, -1, v160
	v_cmp_le_f32_e64 s[4:5], 0, v161
	s_nop 5
	v_fma_f32 v0, -v146, v217, v82
	s_and_b64 vcc, vcc, s[2:3]
	v_cndmask_b32_e32 v0, v230, v0, vcc
	v_fma_f32 v160, -v146, v161, v2
	s_and_b64 vcc, s[4:5], s[2:3]
	v_cndmask_b32_e32 v184, v230, v160, vcc
	v_add_f32_e32 v160, -1.0, v217
	v_add_f32_e32 v161, 0xc2000000, v160
	v_cmp_le_f32_e32 vcc, 0, v160
	v_cmp_le_f32_e64 s[4:5], 0, v161
	v_fma_f32 v160, -v146, v160, v83
	s_and_b64 vcc, vcc, s[2:3]
	v_cndmask_b32_e32 v216, v230, v160, vcc
	v_fma_f32 v160, -v146, v161, v3
	s_and_b64 vcc, s[4:5], s[2:3]
	v_cndmask_b32_e32 v185, v230, v160, vcc
	v_add_f32_e32 v160, -2.0, v217
	v_add_f32_e32 v161, 0xc2000000, v160
	v_cmp_le_f32_e32 vcc, 0, v160
	v_cmp_le_f32_e64 s[4:5], 0, v161
	v_fma_f32 v160, -v146, v160, v84
	s_and_b64 vcc, vcc, s[2:3]
	v_cndmask_b32_e32 v180, v230, v160, vcc
	v_fma_f32 v160, -v146, v161, v4
	s_and_b64 vcc, s[4:5], s[2:3]
	v_cndmask_b32_e32 v186, v230, v160, vcc
	v_add_f32_e32 v160, 0xc0400000, v217
	v_add_f32_e32 v161, 0xc2000000, v160
	v_cmp_le_f32_e32 vcc, 0, v160
	v_cmp_le_f32_e64 s[4:5], 0, v161
	v_fma_f32 v160, -v146, v160, v85
	s_and_b64 vcc, vcc, s[2:3]
	v_cndmask_b32_e32 v181, v230, v160, vcc
	v_fma_f32 v160, -v146, v161, v5
	s_and_b64 vcc, s[4:5], s[2:3]
	v_cndmask_b32_e32 v187, v230, v160, vcc
	v_add_f32_e32 v160, 0xc1000000, v217
	v_add_f32_e32 v161, 0xc2000000, v160
	v_cmp_le_f32_e32 vcc, 0, v160
	v_cmp_le_f32_e64 s[4:5], 0, v161
	v_fma_f32 v160, -v146, v160, v86
	s_and_b64 vcc, vcc, s[2:3]
	v_cndmask_b32_e32 v182, v230, v160, vcc
	v_fma_f32 v160, -v146, v161, v6
	s_and_b64 vcc, s[4:5], s[2:3]
	v_cndmask_b32_e32 v172, v230, v160, vcc
	v_add_f32_e32 v160, 0xc1100000, v217
	v_add_f32_e32 v161, 0xc2000000, v160
	v_cmp_le_f32_e32 vcc, 0, v160
	v_cmp_le_f32_e64 s[4:5], 0, v161
	v_fma_f32 v160, -v146, v160, v87
	s_and_b64 vcc, vcc, s[2:3]
	v_cndmask_b32_e32 v183, v230, v160, vcc
	v_fma_f32 v160, -v146, v161, v7
	s_and_b64 vcc, s[4:5], s[2:3]
	v_cndmask_b32_e32 v173, v230, v160, vcc
	v_add_f32_e32 v160, 0xc1200000, v217
	v_add_f32_e32 v161, 0xc2000000, v160
	v_cmp_le_f32_e32 vcc, 0, v160
	v_cmp_le_f32_e64 s[4:5], 0, v161
	v_fma_f32 v160, -v146, v160, v88
	s_and_b64 vcc, vcc, s[2:3]
	v_cndmask_b32_e32 v178, v230, v160, vcc
	v_fma_f32 v160, -v146, v161, v8
	s_and_b64 vcc, s[4:5], s[2:3]
	v_cndmask_b32_e32 v164, v230, v160, vcc
	v_add_f32_e32 v160, 0xc1300000, v217
	v_add_f32_e32 v161, 0xc2000000, v160
	v_cmp_le_f32_e32 vcc, 0, v160
	v_cmp_le_f32_e64 s[4:5], 0, v161
	v_fma_f32 v160, -v146, v160, v89
	s_and_b64 vcc, vcc, s[2:3]
	v_cndmask_b32_e32 v179, v230, v160, vcc
	v_fma_f32 v160, -v146, v161, v9
	s_and_b64 vcc, s[4:5], s[2:3]
	v_cndmask_b32_e32 v165, v230, v160, vcc
	v_add_f32_e32 v160, 0xc1800000, v217
	v_add_f32_e32 v161, 0xc2000000, v160
	v_cmp_le_f32_e32 vcc, 0, v160
	v_cmp_le_f32_e64 s[4:5], 0, v161
	v_fma_f32 v160, -v146, v160, v90
	s_and_b64 vcc, vcc, s[2:3]
	v_cndmask_b32_e32 v168, v230, v160, vcc
	v_fma_f32 v160, -v146, v161, v10
	s_and_b64 vcc, s[4:5], s[2:3]
	v_cndmask_b32_e32 v166, v230, v160, vcc
	v_add_f32_e32 v160, 0xc1880000, v217
	v_add_f32_e32 v161, 0xc2000000, v160
	v_cmp_le_f32_e32 vcc, 0, v160
	v_cmp_le_f32_e64 s[4:5], 0, v161
	v_fma_f32 v160, -v146, v160, v91
	s_and_b64 vcc, vcc, s[2:3]
	v_cndmask_b32_e32 v169, v230, v160, vcc
	v_fma_f32 v160, -v146, v161, v11
	s_and_b64 vcc, s[4:5], s[2:3]
	v_cndmask_b32_e32 v167, v230, v160, vcc
	v_add_f32_e32 v160, 0xc1900000, v217
	v_add_f32_e32 v161, 0xc2000000, v160
	v_cmp_le_f32_e32 vcc, 0, v160
	v_cmp_le_f32_e64 s[4:5], 0, v161
	v_fma_f32 v160, -v146, v160, v92
	s_and_b64 vcc, vcc, s[2:3]
	v_cndmask_b32_e32 v170, v230, v160, vcc
	v_fma_f32 v160, -v146, v161, v12
	s_and_b64 vcc, s[4:5], s[2:3]
	v_add_f32_e32 v161, 0xc1980000, v217
	v_cndmask_b32_e32 v160, v230, v160, vcc
	v_add_f32_e32 v162, 0xc2000000, v161
	v_cmp_le_f32_e32 vcc, 0, v161
	v_cmp_le_f32_e64 s[4:5], 0, v162
	v_fma_f32 v161, -v146, v161, v93
	s_and_b64 vcc, vcc, s[2:3]
	v_cndmask_b32_e32 v171, v230, v161, vcc
	v_fma_f32 v161, -v146, v162, v13
	s_and_b64 vcc, s[4:5], s[2:3]
	v_add_f32_e32 v162, 0xc1c00000, v217
	v_cndmask_b32_e32 v161, v230, v161, vcc
	v_add_f32_e32 v163, 0xc2000000, v162
	v_cmp_le_f32_e32 vcc, 0, v162
	v_cmp_le_f32_e64 s[4:5], 0, v163
	v_fma_f32 v162, -v146, v162, v94
	s_and_b64 vcc, vcc, s[2:3]
	v_cndmask_b32_e32 v174, v230, v162, vcc
	v_fma_f32 v162, -v146, v163, v14
	s_and_b64 vcc, s[4:5], s[2:3]
	v_add_f32_e32 v163, 0xc1c80000, v217
	v_cndmask_b32_e32 v162, v230, v162, vcc
	v_add_f32_e32 v176, 0xc2000000, v163
	v_cmp_le_f32_e32 vcc, 0, v163
	v_cmp_le_f32_e64 s[4:5], 0, v176
	v_fma_f32 v163, -v146, v163, v95
	s_and_b64 vcc, vcc, s[2:3]
	v_cndmask_b32_e32 v175, v230, v163, vcc
	v_fma_f32 v163, -v146, v176, v15
	s_and_b64 vcc, s[4:5], s[2:3]
	v_add_f32_e32 v176, 0xc1d00000, v217
	v_cndmask_b32_e32 v163, v230, v163, vcc
	v_add_f32_e32 v177, 0xc2000000, v176
	v_cmp_le_f32_e32 vcc, 0, v176
	v_cmp_le_f32_e64 s[4:5], 0, v177
	v_fma_f32 v176, -v146, v176, v96
	s_and_b64 vcc, vcc, s[2:3]
	v_cndmask_b32_e32 v176, v230, v176, vcc
	v_fma_f32 v177, -v146, v177, v16
	s_and_b64 vcc, s[4:5], s[2:3]
	v_cndmask_b32_e32 v214, v230, v177, vcc
	v_add_f32_e32 v177, 0xc1d80000, v217
	v_add_f32_e32 v215, 0xc2000000, v177
	v_cmp_le_f32_e32 vcc, 0, v177
	v_cmp_le_f32_e64 s[4:5], 0, v215
	v_fma_f32 v177, -v146, v177, v97
	s_and_b64 vcc, vcc, s[2:3]
	v_cndmask_b32_e32 v177, v230, v177, vcc
	v_fma_f32 v215, -v146, v215, v17
	s_and_b64 vcc, s[4:5], s[2:3]
	v_cndmask_b32_e32 v215, v230, v215, vcc
	s_mov_b64 s[4:5], 0
